# DN main GEMM (K=2816) K-loop also on the 8-phase ping-pong LDS-DMA schedule
# speedup vs baseline: 1.0475x; 1.0092x over previous
.LBB0_40:
	s_ashr_i32 s2, s10, 31
	s_lshr_b32 s2, s2, 27
	s_add_i32 s2, s10, s2
	s_ashr_i32 s17, s2, 5
	s_andn2_b32 s2, s2, 31
	s_sub_i32 s2, s10, s2
	s_ashr_i32 s3, s2, 31
	s_lshr_b32 s3, s3, 29
	s_add_i32 s3, s2, s3
	s_ashr_i32 s3, s3, 3
	s_lshl_b32 s2, s2, 8
	s_lshl_b32 s14, s17, 11
	s_lshl_b32 s18, s3, 11
	s_add_i32 s2, s2, s14
	s_sub_i32 s14, s18, s2
	s_addk_i32 s14, 0x3f00
	s_lshl_b32 s15, s3, 8
	v_add_u32_e32 v2, s14, v180
	v_add_u32_e32 v15, s15, v180
	v_mad_i64_i32 v[48:49], s[2:3], v15, s5, v[164:165]
	v_mad_i64_i32 v[50:51], s[2:3], v2, s5, v[166:167]
	s_mov_b32 s2, 0x58000
	s_nop 0
	v_add_co_u32_e32 v52, vcc, s2, v50
	s_mov_b32 s3, 0xb0000
	s_nop 0
	v_addc_co_u32_e32 v53, vcc, 0, v51, vcc
	v_add_co_u32_e32 v54, vcc, s3, v50
	v_addc_co_u32_e32 v55, vcc, 0, v51, vcc
	v_add_co_u32_e32 v56, vcc, s2, v48
	s_mov_b32 s2, 0x108000
	s_nop 0
	v_addc_co_u32_e32 v57, vcc, 0, v49, vcc
	v_add_co_u32_e32 v58, vcc, s3, v48
	v_addc_co_u32_e32 v59, vcc, 0, v49, vcc
	v_add_co_u32_e32 v60, vcc, s2, v48
	v_addc_co_u32_e32 v61, vcc, 0, v49, vcc
	v_add_co_u32_e32 v62, vcc, s2, v50
	v_addc_co_u32_e32 v63, vcc, 0, v51, vcc
	s_mulk_i32 s17, 0x1800
	s_add_i32 s17, s18, s17
	v_mov_b32_e32 v2, 0
	v_mad_i64_i32 v[176:177], s[18:19], v15, s5, v[172:173]
	v_add_u32_e32 v15, s17, v190
	s_mov_b64 s[2:3], 0
	s_mov_b32 s16, 1
	v_mov_b32_e32 v3, v2
	v_mov_b32_e32 v4, v2
	v_mov_b32_e32 v5, v2
	v_mov_b32_e32 v6, v2
	v_mov_b32_e32 v7, v2
	v_mov_b32_e32 v8, v2
	v_mov_b32_e32 v9, v2
	v_mov_b32_e32 v10, v2
	v_mov_b32_e32 v11, v2
	v_mov_b32_e32 v12, v2
	v_mov_b32_e32 v13, v2
	v_mov_b32_e32 v14, v2
	v_mad_i64_i32 v[178:179], s[18:19], v15, s5, v[174:175]
	v_mov_b32_e32 v15, v2
	v_mov_b32_e32 v48, v2
	v_mov_b32_e32 v49, v2
	v_mov_b32_e32 v50, v2
	v_mov_b32_e32 v51, v2
	v_mov_b32_e32 v52, v2
	v_mov_b32_e32 v53, v2
	v_mov_b32_e32 v54, v2
	v_mov_b32_e32 v55, v2
	v_mov_b32_e32 v56, v2
	v_mov_b32_e32 v57, v2
	v_mov_b32_e32 v58, v2
	v_mov_b32_e32 v59, v2
	v_mov_b32_e32 v60, v2
	v_mov_b32_e32 v61, v2
	v_mov_b32_e32 v62, v2
	v_mov_b32_e32 v63, v2
	v_mov_b32_e32 v64, v2
	v_mov_b32_e32 v65, v2
	v_mov_b32_e32 v66, v2
	v_mov_b32_e32 v67, v2
	v_mov_b32_e32 v16, v2
	v_mov_b32_e32 v17, v2
	v_mov_b32_e32 v34, v2
	v_mov_b32_e32 v35, v2
	v_mov_b32_e32 v36, v2
	v_mov_b32_e32 v37, v2
	v_mov_b32_e32 v38, v2
	v_mov_b32_e32 v39, v2
	v_mov_b32_e32 v40, v2
	v_mov_b32_e32 v41, v2
	v_mov_b32_e32 v42, v2
	v_mov_b32_e32 v43, v2
	v_mov_b32_e32 v44, v2
	v_mov_b32_e32 v45, v2
	v_mov_b32_e32 v46, v2
	v_mov_b32_e32 v47, v2
	v_mov_b32_e32 v18, v2
	v_mov_b32_e32 v19, v2
	v_mov_b32_e32 v20, v2
	v_mov_b32_e32 v21, v2
	v_mov_b32_e32 v22, v2
	v_mov_b32_e32 v23, v2
	v_mov_b32_e32 v24, v2
	v_mov_b32_e32 v25, v2
	v_mov_b32_e32 v26, v2
	v_mov_b32_e32 v27, v2
	v_mov_b32_e32 v28, v2
	v_mov_b32_e32 v29, v2
	v_mov_b32_e32 v30, v2
	v_mov_b32_e32 v31, v2
	v_mov_b32_e32 v32, v2
	v_mov_b32_e32 v33, v2
	v_mov_b32_e32 v68, v2
	v_mov_b32_e32 v69, v2
	v_mov_b32_e32 v70, v2
	v_mov_b32_e32 v71, v2
	v_mov_b32_e32 v72, v2
	v_mov_b32_e32 v73, v2
	v_mov_b32_e32 v74, v2
	v_mov_b32_e32 v75, v2
	v_mov_b32_e32 v76, v2
	v_mov_b32_e32 v77, v2
	v_mov_b32_e32 v78, v2
	v_mov_b32_e32 v79, v2
	v_mov_b32_e32 v80, v2
	v_mov_b32_e32 v81, v2
	v_mov_b32_e32 v98, v2
	v_mov_b32_e32 v99, v2
	v_mov_b32_e32 v100, v2
	v_mov_b32_e32 v101, v2
	v_mov_b32_e32 v102, v2
	v_mov_b32_e32 v103, v2
	v_mov_b32_e32 v104, v2
	v_mov_b32_e32 v105, v2
	v_mov_b32_e32 v106, v2
	v_mov_b32_e32 v107, v2
	v_mov_b32_e32 v108, v2
	v_mov_b32_e32 v109, v2
	v_mov_b32_e32 v110, v2
	v_mov_b32_e32 v111, v2
	v_mov_b32_e32 v112, v2
	v_mov_b32_e32 v113, v2
	v_mov_b32_e32 v82, v2
	v_mov_b32_e32 v83, v2
	v_mov_b32_e32 v84, v2
	v_mov_b32_e32 v85, v2
	v_mov_b32_e32 v86, v2
	v_mov_b32_e32 v87, v2
	v_mov_b32_e32 v88, v2
	v_mov_b32_e32 v89, v2
	v_mov_b32_e32 v90, v2
	v_mov_b32_e32 v91, v2
	v_mov_b32_e32 v92, v2
	v_mov_b32_e32 v93, v2
	v_mov_b32_e32 v94, v2
	v_mov_b32_e32 v95, v2
	v_mov_b32_e32 v96, v2
	v_mov_b32_e32 v97, v2
	v_mov_b32_e32 v114, v2
	v_mov_b32_e32 v115, v2
	v_mov_b32_e32 v116, v2
	v_mov_b32_e32 v117, v2
	v_mov_b32_e32 v118, v2
	v_mov_b32_e32 v119, v2
	v_mov_b32_e32 v120, v2
	v_mov_b32_e32 v121, v2
	v_mov_b32_e32 v122, v2
	v_mov_b32_e32 v123, v2
	v_mov_b32_e32 v124, v2
	v_mov_b32_e32 v125, v2
	v_mov_b32_e32 v126, v2
	v_mov_b32_e32 v127, v2
	v_mov_b32_e32 v128, v2
	v_mov_b32_e32 v129, v2
	s_mov_b32 s4, 0x22c5000
	s_mov_b32 s12, 0x231d000
	s_mov_b32 s13, 0x2375000
	s_waitcnt lgkmcnt(0)
	v_lshrrev_b32_e32 v130, 6, v200
	v_and_b32_e32 v131, 63, v200
	v_readfirstlane_b32 s17, v130
	s_lshr_b32 s18, s17, 2
	s_and_b32 s19, s17, 3
	s_lshl_b32 s19, s19, 4
	s_lshl_b32 s4, s18, 7
	s_add_u32 s4, s4, s19
	s_add_u32 s19, s4, s14
	s_mul_i32 s19, s19, 5632
	s_add_u32 s2, s36, 0x518d800
	s_addc_u32 s3, s37, 0
	s_add_u32 s2, s2, s19
	s_addc_u32 s3, s3, 0
	s_lshl_b32 s4, s4, 7
	s_lshr_b32 s16, s17, 1
	s_lshl_b32 s16, s16, 6
	s_and_b32 s19, s17, 1
	s_lshl_b32 s19, s19, 4
	s_add_u32 s16, s16, s19
	s_add_u32 s19, s16, s15
	s_mul_i32 s19, s19, 5632
	v_readlane_b32 s13, v255, 30
	s_nop 3
	s_mul_i32 s13, s13, 0x580000
	s_add_u32 s12, s36, s13
	s_addc_u32 s13, s37, 0
	s_add_u32 s12, s12, 0x226d800
	s_addc_u32 s13, s13, 0
	s_add_u32 s12, s12, s19
	s_addc_u32 s13, s13, 0
	s_lshl_b32 s16, s16, 7
	s_add_u32 s16, s16, 0x10000
	v_lshrrev_b32_e32 v132, 3, v131
	v_and_b32_e32 v133, 7, v131
	v_lshrrev_b32_e32 v134, 4, v131
	v_xor_b32_e32 v133, v133, v134
	v_lshlrev_b32_e32 v133, 4, v133
	v_mul_u32_u24_e32 v134, 5632, v132
	v_or_b32_e32 v226, v134, v133
	v_add_u32_e32 v227, 45056, v226
	v_xor_b32_e32 v227, 64, v227
	v_add_u32_e32 v178, 0x58000, v226
	v_add_u32_e32 v179, 0x58000, v227
	v_mul_u32_u24_e32 v134, 5632, v132
	v_or_b32_e32 v228, v134, v133
	v_add_u32_e32 v214, 45056, v228
	v_xor_b32_e32 v214, 64, v214
	v_add_u32_e32 v203, 0x2c000, v228
	v_add_u32_e32 v204, 0x2c000, v214
	v_and_b32_e32 v132, 31, v131
	v_lshrrev_b32_e32 v133, 5, v131
	v_bfe_u32 v134, v132, 1, 3
	v_and_b32_e32 v135, 1, v134
	v_xor_b32_e32 v133, v133, v135
	v_lshlrev_b32_e32 v133, 4, v133
	v_lshl_add_u32 v133, v132, 7, v133
	v_and_b32_e32 v134, 6, v134
	s_lshl_b32 s19, s18, 14
	s_and_b32 s17, s17, 3
	s_lshl_b32 s17, s17, 13
	s_add_u32 s17, s17, 0x10000
	v_xor_b32_e32 v135, 0, v134
	v_lshl_add_u32 v135, v135, 4, v133
	v_add_u32_e32 v246, s19, v135
	v_add_u32_e32 v250, s17, v135
	v_xor_b32_e32 v135, 2, v134
	v_lshl_add_u32 v135, v135, 4, v133
	v_add_u32_e32 v247, s19, v135
	v_add_u32_e32 v251, s17, v135
	v_xor_b32_e32 v135, 4, v134
	v_lshl_add_u32 v135, v135, 4, v133
	v_add_u32_e32 v248, s19, v135
	v_add_u32_e32 v252, s17, v135
	v_xor_b32_e32 v135, 6, v134
	v_lshl_add_u32 v135, v135, 4, v133
	v_add_u32_e32 v249, s19, v135
	v_add_u32_e32 v233, s17, v135
	s_add_u32 m0, s16, 0x0
	s_nop 0
	global_load_lds_dwordx4 v228, s[12:13]
	s_add_u32 m0, s16, 0x400
	s_nop 0
	global_load_lds_dwordx4 v214, s[12:13]
	s_add_u32 m0, s4, 0x0
	s_nop 0
	global_load_lds_dwordx4 v226, s[2:3]
	s_add_u32 m0, s4, 0x400
	s_nop 0
	global_load_lds_dwordx4 v227, s[2:3]
	s_add_u32 m0, s16, 0x1000
	s_nop 0
	global_load_lds_dwordx4 v203, s[12:13]
	s_add_u32 m0, s16, 0x1400
	s_nop 0
	global_load_lds_dwordx4 v204, s[12:13]
	s_add_u32 m0, s4, 0x2000
	s_nop 0
	global_load_lds_dwordx4 v178, s[2:3]
	s_add_u32 m0, s4, 0x2400
	s_nop 0
	global_load_lds_dwordx4 v179, s[2:3]
	s_cmp_lg_u32 s18, 0
	s_cbranch_scc0 .Lgdn_nolag
	s_barrier
.Lgdn_nolag:
	s_waitcnt vmcnt(4)
	s_barrier
	s_add_u32 s12, s12, 0x80
	s_addc_u32 s13, s13, 0
	s_add_u32 m0, s16, 0x8000
	s_nop 0
	global_load_lds_dwordx4 v228, s[12:13]
	s_add_u32 m0, s16, 0x8400
	s_nop 0
	global_load_lds_dwordx4 v214, s[12:13]
	s_add_u32 s2, s2, 0x80
	s_addc_u32 s3, s3, 0
	s_add_u32 m0, s4, 0x8000
	s_nop 0
	global_load_lds_dwordx4 v226, s[2:3]
	s_add_u32 m0, s4, 0x8400
	s_nop 0
	global_load_lds_dwordx4 v227, s[2:3]
	s_add_u32 m0, s16, 0x9000
	s_nop 0
	global_load_lds_dwordx4 v203, s[12:13]
	s_add_u32 m0, s16, 0x9400
	s_nop 0
	global_load_lds_dwordx4 v204, s[12:13]
	s_waitcnt vmcnt(6)
	s_barrier
	s_mov_b32 s17, 0
.Lgdn_loop:
	ds_read_b128 v[192:195], v250
	ds_read_b128 v[196:199], v251
	ds_read_b128 v[208:211], v252
	ds_read_b128 v[218:221], v233
	ds_read_b128 v[130:133], v246 offset:0
	ds_read_b128 v[134:137], v247 offset:0
	ds_read_b128 v[138:141], v248 offset:0
	ds_read_b128 v[142:145], v249 offset:0
	ds_read_b128 v[146:149], v246 offset:4096
	ds_read_b128 v[150:153], v247 offset:4096
	ds_read_b128 v[154:157], v248 offset:4096
	ds_read_b128 v[158:161], v249 offset:4096
	s_add_u32 m0, s4, 0xa000
	s_nop 0
	global_load_lds_dwordx4 v178, s[2:3]
	s_add_u32 m0, s4, 0xa400
	s_nop 0
	global_load_lds_dwordx4 v179, s[2:3]
	s_waitcnt lgkmcnt(8)
	s_barrier
	s_waitcnt lgkmcnt(0)
	s_setprio 1
	v_mfma_f32_32x32x16_bf16 v[114:129], v[192:195], v[130:133], v[114:129]
	v_mfma_f32_32x32x16_bf16 v[82:97], v[192:195], v[146:149], v[82:97]
	v_mfma_f32_32x32x16_bf16 v[114:129], v[196:199], v[134:137], v[114:129]
	v_mfma_f32_32x32x16_bf16 v[82:97], v[196:199], v[150:153], v[82:97]
	v_mfma_f32_32x32x16_bf16 v[114:129], v[208:211], v[138:141], v[114:129]
	v_mfma_f32_32x32x16_bf16 v[82:97], v[208:211], v[154:157], v[82:97]
	v_mfma_f32_32x32x16_bf16 v[114:129], v[218:221], v[142:145], v[114:129]
	v_mfma_f32_32x32x16_bf16 v[82:97], v[218:221], v[158:161], v[82:97]
	s_setprio 0
	s_barrier
	ds_read_b128 v[222:225], v250 offset:4096
	ds_read_b128 v[234:237], v251 offset:4096
	ds_read_b128 v[238:241], v252 offset:4096
	ds_read_b128 v[242:245], v233 offset:4096
	s_add_u32 s12, s12, 0x80
	s_addc_u32 s13, s13, 0
	s_add_u32 m0, s16, 0x0
	s_nop 0
	global_load_lds_dwordx4 v228, s[12:13]
	s_add_u32 m0, s16, 0x400
	s_nop 0
	global_load_lds_dwordx4 v214, s[12:13]
	s_barrier
	s_waitcnt lgkmcnt(0)
	s_setprio 1
	v_mfma_f32_32x32x16_bf16 v[98:113], v[222:225], v[130:133], v[98:113]
	v_mfma_f32_32x32x16_bf16 v[66:81], v[222:225], v[146:149], v[66:81]
	v_mfma_f32_32x32x16_bf16 v[98:113], v[234:237], v[134:137], v[98:113]
	v_mfma_f32_32x32x16_bf16 v[66:81], v[234:237], v[150:153], v[66:81]
	v_mfma_f32_32x32x16_bf16 v[98:113], v[238:241], v[138:141], v[98:113]
	v_mfma_f32_32x32x16_bf16 v[66:81], v[238:241], v[154:157], v[66:81]
	v_mfma_f32_32x32x16_bf16 v[98:113], v[242:245], v[142:145], v[98:113]
	v_mfma_f32_32x32x16_bf16 v[66:81], v[242:245], v[158:161], v[66:81]
	s_setprio 0
	s_barrier
	ds_read_b128 v[130:133], v246 offset:8192
	ds_read_b128 v[134:137], v247 offset:8192
	ds_read_b128 v[138:141], v248 offset:8192
	ds_read_b128 v[142:145], v249 offset:8192
	ds_read_b128 v[146:149], v246 offset:12288
	ds_read_b128 v[150:153], v247 offset:12288
	ds_read_b128 v[154:157], v248 offset:12288
	ds_read_b128 v[158:161], v249 offset:12288
	s_add_u32 s2, s2, 0x80
	s_addc_u32 s3, s3, 0
	s_add_u32 m0, s4, 0x0
	s_nop 0
	global_load_lds_dwordx4 v226, s[2:3]
	s_add_u32 m0, s4, 0x400
	s_nop 0
	global_load_lds_dwordx4 v227, s[2:3]
	s_barrier
	s_waitcnt lgkmcnt(0)
	s_setprio 1
	v_mfma_f32_32x32x16_bf16 v[50:65], v[192:195], v[130:133], v[50:65]
	v_mfma_f32_32x32x16_bf16 v[18:33], v[192:195], v[146:149], v[18:33]
	v_mfma_f32_32x32x16_bf16 v[50:65], v[196:199], v[134:137], v[50:65]
	v_mfma_f32_32x32x16_bf16 v[18:33], v[196:199], v[150:153], v[18:33]
	v_mfma_f32_32x32x16_bf16 v[50:65], v[208:211], v[138:141], v[50:65]
	v_mfma_f32_32x32x16_bf16 v[18:33], v[208:211], v[154:157], v[18:33]
	v_mfma_f32_32x32x16_bf16 v[50:65], v[218:221], v[142:145], v[50:65]
	v_mfma_f32_32x32x16_bf16 v[18:33], v[218:221], v[158:161], v[18:33]
	s_setprio 0
	s_barrier
	s_add_u32 m0, s16, 0x1000
	s_nop 0
	global_load_lds_dwordx4 v203, s[12:13]
	s_add_u32 m0, s16, 0x1400
	s_nop 0
	global_load_lds_dwordx4 v204, s[12:13]
	s_waitcnt vmcnt(6)
	s_barrier
	s_setprio 1
	v_mfma_f32_32x32x16_bf16 v[34:49], v[222:225], v[130:133], v[34:49]
	v_mfma_f32_32x32x16_bf16 v[2:17], v[222:225], v[146:149], v[2:17]
	v_mfma_f32_32x32x16_bf16 v[34:49], v[234:237], v[134:137], v[34:49]
	v_mfma_f32_32x32x16_bf16 v[2:17], v[234:237], v[150:153], v[2:17]
	v_mfma_f32_32x32x16_bf16 v[34:49], v[238:241], v[138:141], v[34:49]
	v_mfma_f32_32x32x16_bf16 v[2:17], v[238:241], v[154:157], v[2:17]
	v_mfma_f32_32x32x16_bf16 v[34:49], v[242:245], v[142:145], v[34:49]
	v_mfma_f32_32x32x16_bf16 v[2:17], v[242:245], v[158:161], v[2:17]
	s_setprio 0
	s_barrier
	ds_read_b128 v[192:195], v250 offset:32768
	ds_read_b128 v[196:199], v251 offset:32768
	ds_read_b128 v[208:211], v252 offset:32768
	ds_read_b128 v[218:221], v233 offset:32768
	ds_read_b128 v[130:133], v246 offset:32768
	ds_read_b128 v[134:137], v247 offset:32768
	ds_read_b128 v[138:141], v248 offset:32768
	ds_read_b128 v[142:145], v249 offset:32768
	ds_read_b128 v[146:149], v246 offset:36864
	ds_read_b128 v[150:153], v247 offset:36864
	ds_read_b128 v[154:157], v248 offset:36864
	ds_read_b128 v[158:161], v249 offset:36864
	s_add_u32 m0, s4, 0x2000
	s_nop 0
	global_load_lds_dwordx4 v178, s[2:3]
	s_add_u32 m0, s4, 0x2400
	s_nop 0
	global_load_lds_dwordx4 v179, s[2:3]
	s_waitcnt lgkmcnt(8)
	s_barrier
	s_waitcnt lgkmcnt(0)
	s_setprio 1
	v_mfma_f32_32x32x16_bf16 v[114:129], v[192:195], v[130:133], v[114:129]
	v_mfma_f32_32x32x16_bf16 v[82:97], v[192:195], v[146:149], v[82:97]
	v_mfma_f32_32x32x16_bf16 v[114:129], v[196:199], v[134:137], v[114:129]
	v_mfma_f32_32x32x16_bf16 v[82:97], v[196:199], v[150:153], v[82:97]
	v_mfma_f32_32x32x16_bf16 v[114:129], v[208:211], v[138:141], v[114:129]
	v_mfma_f32_32x32x16_bf16 v[82:97], v[208:211], v[154:157], v[82:97]
	v_mfma_f32_32x32x16_bf16 v[114:129], v[218:221], v[142:145], v[114:129]
	v_mfma_f32_32x32x16_bf16 v[82:97], v[218:221], v[158:161], v[82:97]
	s_setprio 0
	s_barrier
	ds_read_b128 v[222:225], v250 offset:36864
	ds_read_b128 v[234:237], v251 offset:36864
	ds_read_b128 v[238:241], v252 offset:36864
	ds_read_b128 v[242:245], v233 offset:36864
	s_add_u32 s12, s12, 0x80
	s_addc_u32 s13, s13, 0
	s_add_u32 m0, s16, 0x8000
	s_nop 0
	global_load_lds_dwordx4 v228, s[12:13]
	s_add_u32 m0, s16, 0x8400
	s_nop 0
	global_load_lds_dwordx4 v214, s[12:13]
	s_barrier
	s_waitcnt lgkmcnt(0)
	s_setprio 1
	v_mfma_f32_32x32x16_bf16 v[98:113], v[222:225], v[130:133], v[98:113]
	v_mfma_f32_32x32x16_bf16 v[66:81], v[222:225], v[146:149], v[66:81]
	v_mfma_f32_32x32x16_bf16 v[98:113], v[234:237], v[134:137], v[98:113]
	v_mfma_f32_32x32x16_bf16 v[66:81], v[234:237], v[150:153], v[66:81]
	v_mfma_f32_32x32x16_bf16 v[98:113], v[238:241], v[138:141], v[98:113]
	v_mfma_f32_32x32x16_bf16 v[66:81], v[238:241], v[154:157], v[66:81]
	v_mfma_f32_32x32x16_bf16 v[98:113], v[242:245], v[142:145], v[98:113]
	v_mfma_f32_32x32x16_bf16 v[66:81], v[242:245], v[158:161], v[66:81]
	s_setprio 0
	s_barrier
	ds_read_b128 v[130:133], v246 offset:40960
	ds_read_b128 v[134:137], v247 offset:40960
	ds_read_b128 v[138:141], v248 offset:40960
	ds_read_b128 v[142:145], v249 offset:40960
	ds_read_b128 v[146:149], v246 offset:45056
	ds_read_b128 v[150:153], v247 offset:45056
	ds_read_b128 v[154:157], v248 offset:45056
	ds_read_b128 v[158:161], v249 offset:45056
	s_add_u32 s2, s2, 0x80
	s_addc_u32 s3, s3, 0
	s_add_u32 m0, s4, 0x8000
	s_nop 0
	global_load_lds_dwordx4 v226, s[2:3]
	s_add_u32 m0, s4, 0x8400
	s_nop 0
	global_load_lds_dwordx4 v227, s[2:3]
	s_barrier
	s_waitcnt lgkmcnt(0)
	s_setprio 1
	v_mfma_f32_32x32x16_bf16 v[50:65], v[192:195], v[130:133], v[50:65]
	v_mfma_f32_32x32x16_bf16 v[18:33], v[192:195], v[146:149], v[18:33]
	v_mfma_f32_32x32x16_bf16 v[50:65], v[196:199], v[134:137], v[50:65]
	v_mfma_f32_32x32x16_bf16 v[18:33], v[196:199], v[150:153], v[18:33]
	v_mfma_f32_32x32x16_bf16 v[50:65], v[208:211], v[138:141], v[50:65]
	v_mfma_f32_32x32x16_bf16 v[18:33], v[208:211], v[154:157], v[18:33]
	v_mfma_f32_32x32x16_bf16 v[50:65], v[218:221], v[142:145], v[50:65]
	v_mfma_f32_32x32x16_bf16 v[18:33], v[218:221], v[158:161], v[18:33]
	s_setprio 0
	s_barrier
	s_add_u32 m0, s16, 0x9000
	s_nop 0
	global_load_lds_dwordx4 v203, s[12:13]
	s_add_u32 m0, s16, 0x9400
	s_nop 0
	global_load_lds_dwordx4 v204, s[12:13]
	s_waitcnt vmcnt(6)
	s_barrier
	s_setprio 1
	v_mfma_f32_32x32x16_bf16 v[34:49], v[222:225], v[130:133], v[34:49]
	v_mfma_f32_32x32x16_bf16 v[2:17], v[222:225], v[146:149], v[2:17]
	v_mfma_f32_32x32x16_bf16 v[34:49], v[234:237], v[134:137], v[34:49]
	v_mfma_f32_32x32x16_bf16 v[2:17], v[234:237], v[150:153], v[2:17]
	v_mfma_f32_32x32x16_bf16 v[34:49], v[238:241], v[138:141], v[34:49]
	v_mfma_f32_32x32x16_bf16 v[2:17], v[238:241], v[154:157], v[2:17]
	v_mfma_f32_32x32x16_bf16 v[34:49], v[242:245], v[142:145], v[34:49]
	v_mfma_f32_32x32x16_bf16 v[2:17], v[242:245], v[158:161], v[2:17]
	s_setprio 0
	s_barrier
	s_add_i32 s17, s17, 2
	s_cmp_lt_u32 s17, 42
	s_cbranch_scc1 .Lgdn_loop
	ds_read_b128 v[192:195], v250
	ds_read_b128 v[196:199], v251
	ds_read_b128 v[208:211], v252
	ds_read_b128 v[218:221], v233
	ds_read_b128 v[130:133], v246 offset:0
	ds_read_b128 v[134:137], v247 offset:0
	ds_read_b128 v[138:141], v248 offset:0
	ds_read_b128 v[142:145], v249 offset:0
	ds_read_b128 v[146:149], v246 offset:4096
	ds_read_b128 v[150:153], v247 offset:4096
	ds_read_b128 v[154:157], v248 offset:4096
	ds_read_b128 v[158:161], v249 offset:4096
	s_add_u32 m0, s4, 0xa000
	s_nop 0
	global_load_lds_dwordx4 v178, s[2:3]
	s_add_u32 m0, s4, 0xa400
	s_nop 0
	global_load_lds_dwordx4 v179, s[2:3]
	s_barrier
	s_waitcnt lgkmcnt(0)
	s_setprio 1
	v_mfma_f32_32x32x16_bf16 v[114:129], v[192:195], v[130:133], v[114:129]
	v_mfma_f32_32x32x16_bf16 v[82:97], v[192:195], v[146:149], v[82:97]
	v_mfma_f32_32x32x16_bf16 v[114:129], v[196:199], v[134:137], v[114:129]
	v_mfma_f32_32x32x16_bf16 v[82:97], v[196:199], v[150:153], v[82:97]
	v_mfma_f32_32x32x16_bf16 v[114:129], v[208:211], v[138:141], v[114:129]
	v_mfma_f32_32x32x16_bf16 v[82:97], v[208:211], v[154:157], v[82:97]
	v_mfma_f32_32x32x16_bf16 v[114:129], v[218:221], v[142:145], v[114:129]
	v_mfma_f32_32x32x16_bf16 v[82:97], v[218:221], v[158:161], v[82:97]
	s_setprio 0
	s_barrier
	ds_read_b128 v[222:225], v250 offset:4096
	ds_read_b128 v[234:237], v251 offset:4096
	ds_read_b128 v[238:241], v252 offset:4096
	ds_read_b128 v[242:245], v233 offset:4096
	s_barrier
	s_waitcnt lgkmcnt(0)
	s_setprio 1
	v_mfma_f32_32x32x16_bf16 v[98:113], v[222:225], v[130:133], v[98:113]
	v_mfma_f32_32x32x16_bf16 v[66:81], v[222:225], v[146:149], v[66:81]
	v_mfma_f32_32x32x16_bf16 v[98:113], v[234:237], v[134:137], v[98:113]
	v_mfma_f32_32x32x16_bf16 v[66:81], v[234:237], v[150:153], v[66:81]
	v_mfma_f32_32x32x16_bf16 v[98:113], v[238:241], v[138:141], v[98:113]
	v_mfma_f32_32x32x16_bf16 v[66:81], v[238:241], v[154:157], v[66:81]
	v_mfma_f32_32x32x16_bf16 v[98:113], v[242:245], v[142:145], v[98:113]
	v_mfma_f32_32x32x16_bf16 v[66:81], v[242:245], v[158:161], v[66:81]
	s_setprio 0
	s_barrier
	ds_read_b128 v[130:133], v246 offset:8192
	ds_read_b128 v[134:137], v247 offset:8192
	ds_read_b128 v[138:141], v248 offset:8192
	ds_read_b128 v[142:145], v249 offset:8192
	ds_read_b128 v[146:149], v246 offset:12288
	ds_read_b128 v[150:153], v247 offset:12288
	ds_read_b128 v[154:157], v248 offset:12288
	ds_read_b128 v[158:161], v249 offset:12288
	s_waitcnt vmcnt(4)
	s_barrier
	s_waitcnt lgkmcnt(0)
	s_setprio 1
	v_mfma_f32_32x32x16_bf16 v[50:65], v[192:195], v[130:133], v[50:65]
	v_mfma_f32_32x32x16_bf16 v[18:33], v[192:195], v[146:149], v[18:33]
	v_mfma_f32_32x32x16_bf16 v[50:65], v[196:199], v[134:137], v[50:65]
	v_mfma_f32_32x32x16_bf16 v[18:33], v[196:199], v[150:153], v[18:33]
	v_mfma_f32_32x32x16_bf16 v[50:65], v[208:211], v[138:141], v[50:65]
	v_mfma_f32_32x32x16_bf16 v[18:33], v[208:211], v[154:157], v[18:33]
	v_mfma_f32_32x32x16_bf16 v[50:65], v[218:221], v[142:145], v[50:65]
	v_mfma_f32_32x32x16_bf16 v[18:33], v[218:221], v[158:161], v[18:33]
	s_setprio 0
	s_setprio 1
	v_mfma_f32_32x32x16_bf16 v[34:49], v[222:225], v[130:133], v[34:49]
	v_mfma_f32_32x32x16_bf16 v[2:17], v[222:225], v[146:149], v[2:17]
	v_mfma_f32_32x32x16_bf16 v[34:49], v[234:237], v[134:137], v[34:49]
	v_mfma_f32_32x32x16_bf16 v[2:17], v[234:237], v[150:153], v[2:17]
	v_mfma_f32_32x32x16_bf16 v[34:49], v[238:241], v[138:141], v[34:49]
	v_mfma_f32_32x32x16_bf16 v[2:17], v[238:241], v[154:157], v[2:17]
	v_mfma_f32_32x32x16_bf16 v[34:49], v[242:245], v[142:145], v[34:49]
	v_mfma_f32_32x32x16_bf16 v[2:17], v[242:245], v[158:161], v[2:17]
	s_setprio 0
	s_barrier
	ds_read_b128 v[192:195], v250 offset:32768
	ds_read_b128 v[196:199], v251 offset:32768
	ds_read_b128 v[208:211], v252 offset:32768
	ds_read_b128 v[218:221], v233 offset:32768
	ds_read_b128 v[130:133], v246 offset:32768
	ds_read_b128 v[134:137], v247 offset:32768
	ds_read_b128 v[138:141], v248 offset:32768
	ds_read_b128 v[142:145], v249 offset:32768
	ds_read_b128 v[146:149], v246 offset:36864
	ds_read_b128 v[150:153], v247 offset:36864
	ds_read_b128 v[154:157], v248 offset:36864
	ds_read_b128 v[158:161], v249 offset:36864
	s_waitcnt vmcnt(2)
	s_barrier
	s_waitcnt lgkmcnt(0)
	s_setprio 1
	v_mfma_f32_32x32x16_bf16 v[114:129], v[192:195], v[130:133], v[114:129]
	v_mfma_f32_32x32x16_bf16 v[82:97], v[192:195], v[146:149], v[82:97]
	v_mfma_f32_32x32x16_bf16 v[114:129], v[196:199], v[134:137], v[114:129]
	v_mfma_f32_32x32x16_bf16 v[82:97], v[196:199], v[150:153], v[82:97]
	v_mfma_f32_32x32x16_bf16 v[114:129], v[208:211], v[138:141], v[114:129]
	v_mfma_f32_32x32x16_bf16 v[82:97], v[208:211], v[154:157], v[82:97]
	v_mfma_f32_32x32x16_bf16 v[114:129], v[218:221], v[142:145], v[114:129]
	v_mfma_f32_32x32x16_bf16 v[82:97], v[218:221], v[158:161], v[82:97]
	s_setprio 0
	s_barrier
	ds_read_b128 v[222:225], v250 offset:36864
	ds_read_b128 v[234:237], v251 offset:36864
	ds_read_b128 v[238:241], v252 offset:36864
	ds_read_b128 v[242:245], v233 offset:36864
	s_waitcnt vmcnt(0)
	s_barrier
	s_waitcnt lgkmcnt(0)
	s_setprio 1
	v_mfma_f32_32x32x16_bf16 v[98:113], v[222:225], v[130:133], v[98:113]
	v_mfma_f32_32x32x16_bf16 v[66:81], v[222:225], v[146:149], v[66:81]
	v_mfma_f32_32x32x16_bf16 v[98:113], v[234:237], v[134:137], v[98:113]
	v_mfma_f32_32x32x16_bf16 v[66:81], v[234:237], v[150:153], v[66:81]
	v_mfma_f32_32x32x16_bf16 v[98:113], v[238:241], v[138:141], v[98:113]
	v_mfma_f32_32x32x16_bf16 v[66:81], v[238:241], v[154:157], v[66:81]
	v_mfma_f32_32x32x16_bf16 v[98:113], v[242:245], v[142:145], v[98:113]
	v_mfma_f32_32x32x16_bf16 v[66:81], v[242:245], v[158:161], v[66:81]
	s_setprio 0
	s_barrier
	ds_read_b128 v[130:133], v246 offset:40960
	ds_read_b128 v[134:137], v247 offset:40960
	ds_read_b128 v[138:141], v248 offset:40960
	ds_read_b128 v[142:145], v249 offset:40960
	ds_read_b128 v[146:149], v246 offset:45056
	ds_read_b128 v[150:153], v247 offset:45056
	ds_read_b128 v[154:157], v248 offset:45056
	ds_read_b128 v[158:161], v249 offset:45056
	s_barrier
	s_waitcnt lgkmcnt(0)
	s_setprio 1
	v_mfma_f32_32x32x16_bf16 v[50:65], v[192:195], v[130:133], v[50:65]
	v_mfma_f32_32x32x16_bf16 v[18:33], v[192:195], v[146:149], v[18:33]
	v_mfma_f32_32x32x16_bf16 v[50:65], v[196:199], v[134:137], v[50:65]
	v_mfma_f32_32x32x16_bf16 v[18:33], v[196:199], v[150:153], v[18:33]
	v_mfma_f32_32x32x16_bf16 v[50:65], v[208:211], v[138:141], v[50:65]
	v_mfma_f32_32x32x16_bf16 v[18:33], v[208:211], v[154:157], v[18:33]
	v_mfma_f32_32x32x16_bf16 v[50:65], v[218:221], v[142:145], v[50:65]
	v_mfma_f32_32x32x16_bf16 v[18:33], v[218:221], v[158:161], v[18:33]
	s_setprio 0
	s_setprio 1
	v_mfma_f32_32x32x16_bf16 v[34:49], v[222:225], v[130:133], v[34:49]
	v_mfma_f32_32x32x16_bf16 v[2:17], v[222:225], v[146:149], v[2:17]
	v_mfma_f32_32x32x16_bf16 v[34:49], v[234:237], v[134:137], v[34:49]
	v_mfma_f32_32x32x16_bf16 v[2:17], v[234:237], v[150:153], v[2:17]
	v_mfma_f32_32x32x16_bf16 v[34:49], v[238:241], v[138:141], v[34:49]
	v_mfma_f32_32x32x16_bf16 v[2:17], v[238:241], v[154:157], v[2:17]
	v_mfma_f32_32x32x16_bf16 v[34:49], v[242:245], v[142:145], v[34:49]
	v_mfma_f32_32x32x16_bf16 v[2:17], v[242:245], v[158:161], v[2:17]
	s_setprio 0
	s_barrier
	s_cmp_lg_u32 s18, 0
	s_cbranch_scc1 .Lgdn_nolag2
	s_barrier
.Lgdn_nolag2:
	s_nop 15
	s_nop 15
	s_waitcnt lgkmcnt(3)
	s_waitcnt lgkmcnt(2)
	s_waitcnt lgkmcnt(1)
	s_waitcnt lgkmcnt(0)
	s_waitcnt lgkmcnt(0)
	s_waitcnt lgkmcnt(3)
	s_waitcnt lgkmcnt(2)
	s_waitcnt lgkmcnt(1)
	s_waitcnt lgkmcnt(0)
	s_waitcnt lgkmcnt(0)
	s_waitcnt lgkmcnt(3)
	s_waitcnt lgkmcnt(2)
	s_waitcnt lgkmcnt(1)
	s_waitcnt lgkmcnt(0)
	s_waitcnt lgkmcnt(0)
	v_add_u32_e32 v150, 0x12000, v168
	s_waitcnt lgkmcnt(3)
	s_waitcnt lgkmcnt(2)
	s_waitcnt lgkmcnt(1)
	s_waitcnt lgkmcnt(0)
	s_waitcnt lgkmcnt(0)
	s_waitcnt lgkmcnt(1)
	s_waitcnt lgkmcnt(0)
	s_waitcnt lgkmcnt(0)
	s_waitcnt lgkmcnt(3)
	s_waitcnt lgkmcnt(2)
	s_waitcnt lgkmcnt(1)
	s_waitcnt lgkmcnt(0)
	s_waitcnt lgkmcnt(0)
	s_waitcnt lgkmcnt(3)
	s_waitcnt lgkmcnt(2)
	s_waitcnt lgkmcnt(1)
	s_waitcnt lgkmcnt(0)
	s_waitcnt lgkmcnt(0)
	s_waitcnt lgkmcnt(0)
	s_add_i32 s10, s10, s46
	v_readlane_b32 s2, v254, 52
	s_cmpk_gt_i32 s10, 0xff
	s_nop 0
	v_subrev_u32_e32 v190, s2, v190
	s_nop 6
	v_cvt_pk_bf16_f32 v114, v114, v115
	v_add_u32_e32 v132, s14, v181
	v_or_b32_e32 v130, s15, v171
	v_ashrrev_i32_e32 v133, 31, v132
	v_ashrrev_i32_e32 v131, 31, v130
	v_lshlrev_b64 v[130:131], 1, v[130:131]
	v_cvt_pk_bf16_f32 v115, v116, v117
	s_nop 5
	v_cvt_pk_bf16_f32 v98, v98, v99
	v_cvt_pk_bf16_f32 v99, v100, v101
	v_lshlrev_b64 v[134:135], 11, v[132:133]
	v_lshl_add_u64 v[134:135], s[80:81], 0, v[134:135]
	v_lshl_add_u64 v[134:135], v[134:135], 0, v[130:131]
	v_lshl_add_u64 v[134:135], v[134:135], 0, v[0:1]
	global_store_dwordx2 v[134:135], v[98:99], off offset:64
	v_cvt_pk_bf16_f32 v98, v102, v103
	v_cvt_pk_bf16_f32 v99, v104, v105
	global_store_dwordx2 v[134:135], v[98:99], off offset:80
	v_cvt_pk_bf16_f32 v98, v106, v107
	v_cvt_pk_bf16_f32 v99, v108, v109
	global_store_dwordx2 v[134:135], v[98:99], off offset:96
	v_cvt_pk_bf16_f32 v98, v110, v111
	v_cvt_pk_bf16_f32 v99, v112, v113
	global_store_dwordx2 v[134:135], v[98:99], off offset:112
	v_or_b32_e32 v98, 32, v132
	v_ashrrev_i32_e32 v99, 31, v98
	v_lshlrev_b64 v[98:99], 11, v[98:99]
	v_lshl_add_u64 v[98:99], s[80:81], 0, v[98:99]
	v_lshl_add_u64 v[98:99], v[98:99], 0, v[130:131]
	v_lshl_add_u64 v[98:99], v[98:99], 0, v[0:1]
	v_cvt_pk_bf16_f32 v66, v66, v67
	v_cvt_pk_bf16_f32 v67, v68, v69
	global_store_dwordx2 v[98:99], v[66:67], off offset:64
	v_cvt_pk_bf16_f32 v66, v70, v71
	v_cvt_pk_bf16_f32 v67, v72, v73
	global_store_dwordx2 v[98:99], v[66:67], off offset:80
	v_cvt_pk_bf16_f32 v66, v74, v75
	v_cvt_pk_bf16_f32 v67, v76, v77
	global_store_dwordx2 v[98:99], v[66:67], off offset:96
	v_cvt_pk_bf16_f32 v66, v78, v79
	v_cvt_pk_bf16_f32 v67, v80, v81
	global_store_dwordx2 v[98:99], v[66:67], off offset:112
	v_or_b32_e32 v66, 64, v132
	v_ashrrev_i32_e32 v67, 31, v66
	v_lshlrev_b64 v[66:67], 11, v[66:67]
	v_lshl_add_u64 v[66:67], s[80:81], 0, v[66:67]
	v_lshl_add_u64 v[66:67], v[66:67], 0, v[130:131]
	v_lshl_add_u64 v[66:67], v[66:67], 0, v[0:1]
	v_cvt_pk_bf16_f32 v34, v34, v35
	v_cvt_pk_bf16_f32 v35, v36, v37
	global_store_dwordx2 v[66:67], v[34:35], off offset:64
	v_cvt_pk_bf16_f32 v34, v38, v39
	v_cvt_pk_bf16_f32 v35, v40, v41
	global_store_dwordx2 v[66:67], v[34:35], off offset:80
	v_cvt_pk_bf16_f32 v34, v42, v43
	v_cvt_pk_bf16_f32 v35, v44, v45
	global_store_dwordx2 v[66:67], v[34:35], off offset:96
	v_cvt_pk_bf16_f32 v34, v46, v47
	v_cvt_pk_bf16_f32 v35, v48, v49
	global_store_dwordx2 v[66:67], v[34:35], off offset:112
	v_or_b32_e32 v34, 0x60, v132
	v_ashrrev_i32_e32 v35, 31, v34
	v_lshlrev_b64 v[34:35], 11, v[34:35]
	v_lshl_add_u64 v[34:35], s[80:81], 0, v[34:35]
	v_lshl_add_u64 v[34:35], v[34:35], 0, v[130:131]
	v_cvt_pk_bf16_f32 v82, v82, v83
	v_cvt_pk_bf16_f32 v83, v84, v85
	v_cvt_pk_bf16_f32 v50, v50, v51
	v_cvt_pk_bf16_f32 v51, v52, v53
	v_lshl_add_u64 v[34:35], v[34:35], 0, v[0:1]
	v_cvt_pk_bf16_f32 v18, v18, v19
	v_cvt_pk_bf16_f32 v19, v20, v21
	s_nop 3
	v_cvt_pk_bf16_f32 v2, v2, v3
	v_cvt_pk_bf16_f32 v3, v4, v5
	global_store_dwordx2 v[134:135], v[114:115], off
	v_cvt_pk_bf16_f32 v114, v118, v119
	v_cvt_pk_bf16_f32 v115, v120, v121
	global_store_dwordx2 v[98:99], v[82:83], off
	v_cvt_pk_bf16_f32 v82, v86, v87
	v_cvt_pk_bf16_f32 v83, v88, v89
	global_store_dwordx2 v[66:67], v[50:51], off
	v_cvt_pk_bf16_f32 v50, v54, v55
	v_cvt_pk_bf16_f32 v51, v56, v57
	global_store_dwordx2 v[34:35], v[18:19], off
	v_cvt_pk_bf16_f32 v18, v22, v23
	v_cvt_pk_bf16_f32 v19, v24, v25
	global_store_dwordx2 v[34:35], v[2:3], off offset:64
	v_cvt_pk_bf16_f32 v2, v6, v7
	v_cvt_pk_bf16_f32 v3, v8, v9
	global_store_dwordx2 v[134:135], v[114:115], off offset:16
	v_cvt_pk_bf16_f32 v114, v122, v123
	v_cvt_pk_bf16_f32 v115, v124, v125
	global_store_dwordx2 v[98:99], v[82:83], off offset:16
	v_cvt_pk_bf16_f32 v82, v90, v91
	v_cvt_pk_bf16_f32 v83, v92, v93
	global_store_dwordx2 v[66:67], v[50:51], off offset:16
	v_cvt_pk_bf16_f32 v50, v58, v59
	v_cvt_pk_bf16_f32 v51, v60, v61
	global_store_dwordx2 v[34:35], v[18:19], off offset:16
	v_cvt_pk_bf16_f32 v18, v26, v27
	v_cvt_pk_bf16_f32 v19, v28, v29
	global_store_dwordx2 v[34:35], v[2:3], off offset:80
	v_cvt_pk_bf16_f32 v2, v10, v11
	v_cvt_pk_bf16_f32 v3, v12, v13
	global_store_dwordx2 v[134:135], v[114:115], off offset:32
	v_cvt_pk_bf16_f32 v114, v126, v127
	v_cvt_pk_bf16_f32 v115, v128, v129
	global_store_dwordx2 v[98:99], v[82:83], off offset:32
	v_cvt_pk_bf16_f32 v82, v94, v95
	v_cvt_pk_bf16_f32 v83, v96, v97
	global_store_dwordx2 v[66:67], v[50:51], off offset:32
	v_cvt_pk_bf16_f32 v50, v62, v63
	v_cvt_pk_bf16_f32 v51, v64, v65
	global_store_dwordx2 v[34:35], v[18:19], off offset:32
	v_cvt_pk_bf16_f32 v18, v30, v31
	v_cvt_pk_bf16_f32 v19, v32, v33
	global_store_dwordx2 v[34:35], v[2:3], off offset:96
	v_cvt_pk_bf16_f32 v2, v14, v15
	v_cvt_pk_bf16_f32 v3, v16, v17
	global_store_dwordx2 v[134:135], v[114:115], off offset:48
	global_store_dwordx2 v[98:99], v[82:83], off offset:48
	global_store_dwordx2 v[66:67], v[50:51], off offset:48
	global_store_dwordx2 v[34:35], v[18:19], off offset:48
	global_store_dwordx2 v[34:35], v[2:3], off offset:112
	s_cbranch_scc0 .LBB0_40

.LBB0_53:
	s_mul_hi_i32 s2, s10, 0x2e8ba2e9
	s_lshr_b32 s3, s2, 31
	s_ashr_i32 s2, s2, 5
	s_add_i32 s17, s2, s3
	s_lshl_b32 s2, s17, 3
	s_sub_i32 s3, s0, s2
	s_min_i32 s3, s3, 8
	s_abs_i32 s14, s3
	v_cvt_f32_u32_e32 v2, s14
	s_sub_i32 s19, 0, s14
	s_mul_i32 s15, s17, 0xffffff50
	s_add_i32 s15, s15, s10
	v_rcp_iflag_f32_e32 v2, v2
	s_abs_i32 s16, s15
	s_xor_b32 s18, s15, s3
	s_ashr_i32 s18, s18, 31
	v_mul_f32_e32 v2, 0x4f7ffffe, v2
	v_cvt_u32_f32_e32 v2, v2
	s_mulk_i32 s17, 0xa8
	s_mov_b32 s4, 0x308d000
	s_mov_b32 s6, 0x30ad000
	v_readfirstlane_b32 s22, v2
	s_mul_i32 s19, s19, s22
	s_mul_hi_u32 s19, s22, s19
	s_add_i32 s22, s22, s19
	s_mul_hi_u32 s19, s16, s22
	s_mul_i32 s22, s19, s14
	s_sub_i32 s16, s16, s22
	s_add_i32 s23, s19, 1
	s_sub_i32 s22, s16, s14
	s_cmp_ge_u32 s16, s14
	s_cselect_b32 s19, s23, s19
	s_cselect_b32 s16, s22, s16
	s_add_i32 s22, s19, 1
	s_cmp_ge_u32 s16, s14
	s_cselect_b32 s14, s22, s19
	s_xor_b32 s14, s14, s18
	s_sub_i32 s16, s14, s18
	s_mul_i32 s18, s16, s3
	s_add_i32 s15, s15, s2
	s_sub_i32 s2, s15, s18
	s_lshl_b32 s14, s2, 8
	v_add_u32_e32 v2, s14, v164
	v_ashrrev_i32_e32 v3, 31, v2
	v_lshlrev_b64 v[2:3], 11, v[2:3]
	s_lshl_b32 s15, s16, 8
	v_lshl_add_u64 v[52:53], v[168:169], 0, v[2:3]
	s_mov_b32 s2, 0x20000
	v_add_u32_e32 v4, s15, v164
	v_add_co_u32_e32 v54, vcc, s2, v52
	v_ashrrev_i32_e32 v5, 31, v4
	s_nop 0
	v_addc_co_u32_e32 v55, vcc, 0, v53, vcc
	s_mov_b32 s3, 0x40000
	v_lshlrev_b64 v[48:49], 11, v[4:5]
	v_add_co_u32_e32 v56, vcc, s3, v52
	v_lshl_add_u64 v[50:51], v[166:167], 0, v[48:49]
	s_nop 0
	v_addc_co_u32_e32 v57, vcc, 0, v53, vcc
	v_add_co_u32_e32 v58, vcc, s2, v50
	s_mov_b32 s2, 0x60000
	s_nop 0
	v_addc_co_u32_e32 v59, vcc, 0, v51, vcc
	v_add_co_u32_e32 v60, vcc, s3, v50
	v_addc_co_u32_e32 v61, vcc, 0, v51, vcc
	v_add_co_u32_e32 v62, vcc, s2, v50
	v_addc_co_u32_e32 v63, vcc, 0, v51, vcc
	v_add_co_u32_e32 v64, vcc, s2, v52
	v_addc_co_u32_e32 v65, vcc, 0, v53, vcc
	s_sub_i32 s18, s10, s18
	s_sub_i32 s17, s18, s17
	s_lshl_b32 s18, s17, 8
	s_ashr_i32 s19, s18, 31
	v_lshl_add_u64 v[178:179], v[174:175], 0, v[48:49]
	v_lshl_add_u64 v[48:49], v[164:165], 0, s[18:19]
	v_mov_b32_e32 v2, 0
	v_lshlrev_b64 v[48:49], 11, v[48:49]
	s_mov_b32 s16, 1
	s_mov_b64 s[2:3], 0
	v_mov_b32_e32 v3, v2
	v_mov_b32_e32 v4, v2
	v_mov_b32_e32 v5, v2
	v_mov_b32_e32 v6, v2
	v_mov_b32_e32 v7, v2
	v_mov_b32_e32 v8, v2
	v_mov_b32_e32 v9, v2
	v_mov_b32_e32 v10, v2
	v_mov_b32_e32 v11, v2
	v_mov_b32_e32 v12, v2
	v_mov_b32_e32 v13, v2
	v_mov_b32_e32 v14, v2
	v_mov_b32_e32 v15, v2
	v_lshl_add_u64 v[180:181], v[176:177], 0, v[48:49]
	v_mov_b32_e32 v48, v2
	v_mov_b32_e32 v49, v2
	v_mov_b32_e32 v50, v2
	v_mov_b32_e32 v51, v2
	v_mov_b32_e32 v52, v2
	v_mov_b32_e32 v53, v2
	v_mov_b32_e32 v54, v2
	v_mov_b32_e32 v55, v2
	v_mov_b32_e32 v56, v2
	v_mov_b32_e32 v57, v2
	v_mov_b32_e32 v58, v2
	v_mov_b32_e32 v59, v2
	v_mov_b32_e32 v60, v2
	v_mov_b32_e32 v61, v2
	v_mov_b32_e32 v62, v2
	v_mov_b32_e32 v63, v2
	v_mov_b32_e32 v16, v2
	v_mov_b32_e32 v17, v2
	v_mov_b32_e32 v34, v2
	v_mov_b32_e32 v35, v2
	v_mov_b32_e32 v36, v2
	v_mov_b32_e32 v37, v2
	v_mov_b32_e32 v38, v2
	v_mov_b32_e32 v39, v2
	v_mov_b32_e32 v40, v2
	v_mov_b32_e32 v41, v2
	v_mov_b32_e32 v42, v2
	v_mov_b32_e32 v43, v2
	v_mov_b32_e32 v44, v2
	v_mov_b32_e32 v45, v2
	v_mov_b32_e32 v46, v2
	v_mov_b32_e32 v47, v2
	v_mov_b32_e32 v18, v2
	v_mov_b32_e32 v19, v2
	v_mov_b32_e32 v20, v2
	v_mov_b32_e32 v21, v2
	v_mov_b32_e32 v22, v2
	v_mov_b32_e32 v23, v2
	v_mov_b32_e32 v24, v2
	v_mov_b32_e32 v25, v2
	v_mov_b32_e32 v26, v2
	v_mov_b32_e32 v27, v2
	v_mov_b32_e32 v28, v2
	v_mov_b32_e32 v29, v2
	v_mov_b32_e32 v30, v2
	v_mov_b32_e32 v31, v2
	v_mov_b32_e32 v32, v2
	v_mov_b32_e32 v33, v2
	v_mov_b32_e32 v64, v2
	v_mov_b32_e32 v65, v2
	v_mov_b32_e32 v66, v2
	v_mov_b32_e32 v67, v2
	v_mov_b32_e32 v68, v2
	v_mov_b32_e32 v69, v2
	v_mov_b32_e32 v70, v2
	v_mov_b32_e32 v71, v2
	v_mov_b32_e32 v72, v2
	v_mov_b32_e32 v73, v2
	v_mov_b32_e32 v74, v2
	v_mov_b32_e32 v75, v2
	v_mov_b32_e32 v76, v2
	v_mov_b32_e32 v77, v2
	v_mov_b32_e32 v78, v2
	v_mov_b32_e32 v79, v2
	v_mov_b32_e32 v80, v2
	v_mov_b32_e32 v81, v2
	v_mov_b32_e32 v98, v2
	v_mov_b32_e32 v99, v2
	v_mov_b32_e32 v100, v2
	v_mov_b32_e32 v101, v2
	v_mov_b32_e32 v102, v2
	v_mov_b32_e32 v103, v2
	v_mov_b32_e32 v104, v2
	v_mov_b32_e32 v105, v2
	v_mov_b32_e32 v106, v2
	v_mov_b32_e32 v107, v2
	v_mov_b32_e32 v108, v2
	v_mov_b32_e32 v109, v2
	v_mov_b32_e32 v110, v2
	v_mov_b32_e32 v111, v2
	v_mov_b32_e32 v112, v2
	v_mov_b32_e32 v113, v2
	v_mov_b32_e32 v82, v2
	v_mov_b32_e32 v83, v2
	v_mov_b32_e32 v84, v2
	v_mov_b32_e32 v85, v2
	v_mov_b32_e32 v86, v2
	v_mov_b32_e32 v87, v2
	v_mov_b32_e32 v88, v2
	v_mov_b32_e32 v89, v2
	v_mov_b32_e32 v90, v2
	v_mov_b32_e32 v91, v2
	v_mov_b32_e32 v92, v2
	v_mov_b32_e32 v93, v2
	v_mov_b32_e32 v94, v2
	v_mov_b32_e32 v95, v2
	v_mov_b32_e32 v96, v2
	v_mov_b32_e32 v97, v2
	v_mov_b32_e32 v114, v2
	v_mov_b32_e32 v115, v2
	v_mov_b32_e32 v116, v2
	v_mov_b32_e32 v117, v2
	v_mov_b32_e32 v118, v2
	v_mov_b32_e32 v119, v2
	v_mov_b32_e32 v120, v2
	v_mov_b32_e32 v121, v2
	v_mov_b32_e32 v122, v2
	v_mov_b32_e32 v123, v2
	v_mov_b32_e32 v124, v2
	v_mov_b32_e32 v125, v2
	v_mov_b32_e32 v126, v2
	v_mov_b32_e32 v127, v2
	v_mov_b32_e32 v128, v2
	v_mov_b32_e32 v129, v2
	s_mov_b32 s7, 0x30cd000
	s_waitcnt lgkmcnt(0)
	v_lshrrev_b32_e32 v130, 6, v200
	v_and_b32_e32 v131, 63, v200
	v_readfirstlane_b32 s17, v130
	s_lshr_b32 s18, s17, 2
	s_and_b32 s19, s17, 3
	s_lshl_b32 s19, s19, 4
	s_lshl_b32 s4, s18, 7
	s_add_u32 s4, s4, s19
	s_add_u32 s19, s4, s14
	s_mul_i32 s19, s19, 2048
	s_add_u32 s2, s36, 0x308d800
	s_addc_u32 s3, s37, 0
	s_add_u32 s2, s2, s19
	s_addc_u32 s3, s3, 0
	s_lshl_b32 s4, s4, 7
	s_lshr_b32 s16, s17, 1
	s_lshl_b32 s16, s16, 6
	s_and_b32 s19, s17, 1
	s_lshl_b32 s19, s19, 4
	s_add_u32 s16, s16, s19
	s_add_u32 s19, s16, s15
	s_mul_i32 s19, s19, 2048
	v_readlane_b32 s7, v255, 30
	s_nop 3
	s_mul_i32 s7, s7, 0xb00000
	s_add_u32 s6, s36, s7
	s_addc_u32 s7, s37, 0
	s_add_u32 s6, s6, 0xc6d800
	s_addc_u32 s7, s7, 0
	s_add_u32 s6, s6, s19
	s_addc_u32 s7, s7, 0
	s_lshl_b32 s16, s16, 7
	s_add_u32 s16, s16, 0x10000
	v_lshrrev_b32_e32 v132, 3, v131
	v_and_b32_e32 v133, 7, v131
	v_lshrrev_b32_e32 v134, 4, v131
	v_xor_b32_e32 v133, v133, v134
	v_lshlrev_b32_e32 v133, 4, v133
	v_mul_u32_u24_e32 v134, 2048, v132
	v_or_b32_e32 v226, v134, v133
	v_add_u32_e32 v227, 16384, v226
	v_xor_b32_e32 v227, 64, v227
	v_add_u32_e32 v178, 0x20000, v226
	v_add_u32_e32 v179, 0x20000, v227
	v_mul_u32_u24_e32 v134, 2048, v132
	v_or_b32_e32 v228, v134, v133
	v_add_u32_e32 v214, 16384, v228
	v_xor_b32_e32 v214, 64, v214
	v_add_u32_e32 v203, 0x10000, v228
	v_add_u32_e32 v204, 0x10000, v214
	v_and_b32_e32 v132, 31, v131
	v_lshrrev_b32_e32 v133, 5, v131
	v_bfe_u32 v134, v132, 1, 3
	v_and_b32_e32 v135, 1, v134
	v_xor_b32_e32 v133, v133, v135
	v_lshlrev_b32_e32 v133, 4, v133
	v_lshl_add_u32 v133, v132, 7, v133
	v_and_b32_e32 v134, 6, v134
	s_lshl_b32 s19, s18, 14
	s_and_b32 s17, s17, 3
	s_lshl_b32 s17, s17, 13
	s_add_u32 s17, s17, 0x10000
	v_xor_b32_e32 v135, 0, v134
	v_lshl_add_u32 v135, v135, 4, v133
	v_add_u32_e32 v246, s19, v135
	v_add_u32_e32 v250, s17, v135
	v_xor_b32_e32 v135, 2, v134
	v_lshl_add_u32 v135, v135, 4, v133
	v_add_u32_e32 v247, s19, v135
	v_add_u32_e32 v251, s17, v135
	v_xor_b32_e32 v135, 4, v134
	v_lshl_add_u32 v135, v135, 4, v133
	v_add_u32_e32 v248, s19, v135
	v_add_u32_e32 v252, s17, v135
	v_xor_b32_e32 v135, 6, v134
	v_lshl_add_u32 v135, v135, 4, v133
	v_add_u32_e32 v249, s19, v135
	v_add_u32_e32 v233, s17, v135
	s_add_u32 m0, s16, 0x0
	s_nop 0
	global_load_lds_dwordx4 v228, s[6:7]
	s_add_u32 m0, s16, 0x400
	s_nop 0
	global_load_lds_dwordx4 v214, s[6:7]
	s_add_u32 m0, s4, 0x0
	s_nop 0
	global_load_lds_dwordx4 v226, s[2:3]
	s_add_u32 m0, s4, 0x400
	s_nop 0
	global_load_lds_dwordx4 v227, s[2:3]
	s_add_u32 m0, s16, 0x1000
	s_nop 0
	global_load_lds_dwordx4 v203, s[6:7]
	s_add_u32 m0, s16, 0x1400
	s_nop 0
	global_load_lds_dwordx4 v204, s[6:7]
	s_add_u32 m0, s4, 0x2000
	s_nop 0
	global_load_lds_dwordx4 v178, s[2:3]
	s_add_u32 m0, s4, 0x2400
	s_nop 0
	global_load_lds_dwordx4 v179, s[2:3]
	s_cmp_lg_u32 s18, 0
	s_cbranch_scc0 .Lggu_nolag
	s_barrier
.Lggu_nolag:
	s_waitcnt vmcnt(4)
	s_barrier
	s_add_u32 s6, s6, 0x80
	s_addc_u32 s7, s7, 0
	s_add_u32 m0, s16, 0x8000
	s_nop 0
	global_load_lds_dwordx4 v228, s[6:7]
	s_add_u32 m0, s16, 0x8400
	s_nop 0
	global_load_lds_dwordx4 v214, s[6:7]
	s_add_u32 s2, s2, 0x80
	s_addc_u32 s3, s3, 0
	s_add_u32 m0, s4, 0x8000
	s_nop 0
	global_load_lds_dwordx4 v226, s[2:3]
	s_add_u32 m0, s4, 0x8400
	s_nop 0
	global_load_lds_dwordx4 v227, s[2:3]
	s_add_u32 m0, s16, 0x9000
	s_nop 0
	global_load_lds_dwordx4 v203, s[6:7]
	s_add_u32 m0, s16, 0x9400
	s_nop 0
	global_load_lds_dwordx4 v204, s[6:7]
	s_waitcnt vmcnt(6)
	s_barrier
	s_mov_b32 s17, 0
.Lggu_loop:
	ds_read_b128 v[192:195], v250
	ds_read_b128 v[196:199], v251
	ds_read_b128 v[208:211], v252
	ds_read_b128 v[218:221], v233
	ds_read_b128 v[130:133], v246 offset:0
	ds_read_b128 v[134:137], v247 offset:0
	ds_read_b128 v[138:141], v248 offset:0
	ds_read_b128 v[142:145], v249 offset:0
	ds_read_b128 v[146:149], v246 offset:4096
	ds_read_b128 v[150:153], v247 offset:4096
	ds_read_b128 v[154:157], v248 offset:4096
	ds_read_b128 v[158:161], v249 offset:4096
	s_add_u32 m0, s4, 0xa000
	s_nop 0
	global_load_lds_dwordx4 v178, s[2:3]
	s_add_u32 m0, s4, 0xa400
	s_nop 0
	global_load_lds_dwordx4 v179, s[2:3]
	s_waitcnt lgkmcnt(8)
	s_barrier
	s_waitcnt lgkmcnt(0)
	s_setprio 1
	v_mfma_f32_32x32x16_bf16 v[114:129], v[192:195], v[130:133], v[114:129]
	v_mfma_f32_32x32x16_bf16 v[82:97], v[192:195], v[146:149], v[82:97]
	v_mfma_f32_32x32x16_bf16 v[114:129], v[196:199], v[134:137], v[114:129]
	v_mfma_f32_32x32x16_bf16 v[82:97], v[196:199], v[150:153], v[82:97]
	v_mfma_f32_32x32x16_bf16 v[114:129], v[208:211], v[138:141], v[114:129]
	v_mfma_f32_32x32x16_bf16 v[82:97], v[208:211], v[154:157], v[82:97]
	v_mfma_f32_32x32x16_bf16 v[114:129], v[218:221], v[142:145], v[114:129]
	v_mfma_f32_32x32x16_bf16 v[82:97], v[218:221], v[158:161], v[82:97]
	s_setprio 0
	s_barrier
	ds_read_b128 v[222:225], v250 offset:4096
	ds_read_b128 v[234:237], v251 offset:4096
	ds_read_b128 v[238:241], v252 offset:4096
	ds_read_b128 v[242:245], v233 offset:4096
	s_add_u32 s6, s6, 0x80
	s_addc_u32 s7, s7, 0
	s_add_u32 m0, s16, 0x0
	s_nop 0
	global_load_lds_dwordx4 v228, s[6:7]
	s_add_u32 m0, s16, 0x400
	s_nop 0
	global_load_lds_dwordx4 v214, s[6:7]
	s_barrier
	s_waitcnt lgkmcnt(0)
	s_setprio 1
	v_mfma_f32_32x32x16_bf16 v[98:113], v[222:225], v[130:133], v[98:113]
	v_mfma_f32_32x32x16_bf16 v[66:81], v[222:225], v[146:149], v[66:81]
	v_mfma_f32_32x32x16_bf16 v[98:113], v[234:237], v[134:137], v[98:113]
	v_mfma_f32_32x32x16_bf16 v[66:81], v[234:237], v[150:153], v[66:81]
	v_mfma_f32_32x32x16_bf16 v[98:113], v[238:241], v[138:141], v[98:113]
	v_mfma_f32_32x32x16_bf16 v[66:81], v[238:241], v[154:157], v[66:81]
	v_mfma_f32_32x32x16_bf16 v[98:113], v[242:245], v[142:145], v[98:113]
	v_mfma_f32_32x32x16_bf16 v[66:81], v[242:245], v[158:161], v[66:81]
	s_setprio 0
	s_barrier
	ds_read_b128 v[130:133], v246 offset:8192
	ds_read_b128 v[134:137], v247 offset:8192
	ds_read_b128 v[138:141], v248 offset:8192
	ds_read_b128 v[142:145], v249 offset:8192
	ds_read_b128 v[146:149], v246 offset:12288
	ds_read_b128 v[150:153], v247 offset:12288
	ds_read_b128 v[154:157], v248 offset:12288
	ds_read_b128 v[158:161], v249 offset:12288
	s_add_u32 s2, s2, 0x80
	s_addc_u32 s3, s3, 0
	s_add_u32 m0, s4, 0x0
	s_nop 0
	global_load_lds_dwordx4 v226, s[2:3]
	s_add_u32 m0, s4, 0x400
	s_nop 0
	global_load_lds_dwordx4 v227, s[2:3]
	s_barrier
	s_waitcnt lgkmcnt(0)
	s_setprio 1
	v_mfma_f32_32x32x16_bf16 v[50:65], v[192:195], v[130:133], v[50:65]
	v_mfma_f32_32x32x16_bf16 v[18:33], v[192:195], v[146:149], v[18:33]
	v_mfma_f32_32x32x16_bf16 v[50:65], v[196:199], v[134:137], v[50:65]
	v_mfma_f32_32x32x16_bf16 v[18:33], v[196:199], v[150:153], v[18:33]
	v_mfma_f32_32x32x16_bf16 v[50:65], v[208:211], v[138:141], v[50:65]
	v_mfma_f32_32x32x16_bf16 v[18:33], v[208:211], v[154:157], v[18:33]
	v_mfma_f32_32x32x16_bf16 v[50:65], v[218:221], v[142:145], v[50:65]
	v_mfma_f32_32x32x16_bf16 v[18:33], v[218:221], v[158:161], v[18:33]
	s_setprio 0
	s_barrier
	s_add_u32 m0, s16, 0x1000
	s_nop 0
	global_load_lds_dwordx4 v203, s[6:7]
	s_add_u32 m0, s16, 0x1400
	s_nop 0
	global_load_lds_dwordx4 v204, s[6:7]
	s_waitcnt vmcnt(6)
	s_barrier
	s_setprio 1
	v_mfma_f32_32x32x16_bf16 v[34:49], v[222:225], v[130:133], v[34:49]
	v_mfma_f32_32x32x16_bf16 v[2:17], v[222:225], v[146:149], v[2:17]
	v_mfma_f32_32x32x16_bf16 v[34:49], v[234:237], v[134:137], v[34:49]
	v_mfma_f32_32x32x16_bf16 v[2:17], v[234:237], v[150:153], v[2:17]
	v_mfma_f32_32x32x16_bf16 v[34:49], v[238:241], v[138:141], v[34:49]
	v_mfma_f32_32x32x16_bf16 v[2:17], v[238:241], v[154:157], v[2:17]
	v_mfma_f32_32x32x16_bf16 v[34:49], v[242:245], v[142:145], v[34:49]
	v_mfma_f32_32x32x16_bf16 v[2:17], v[242:245], v[158:161], v[2:17]
	s_setprio 0
	s_barrier
	ds_read_b128 v[192:195], v250 offset:32768
	ds_read_b128 v[196:199], v251 offset:32768
	ds_read_b128 v[208:211], v252 offset:32768
	ds_read_b128 v[218:221], v233 offset:32768
	ds_read_b128 v[130:133], v246 offset:32768
	ds_read_b128 v[134:137], v247 offset:32768
	ds_read_b128 v[138:141], v248 offset:32768
	ds_read_b128 v[142:145], v249 offset:32768
	ds_read_b128 v[146:149], v246 offset:36864
	ds_read_b128 v[150:153], v247 offset:36864
	ds_read_b128 v[154:157], v248 offset:36864
	ds_read_b128 v[158:161], v249 offset:36864
	s_add_u32 m0, s4, 0x2000
	s_nop 0
	global_load_lds_dwordx4 v178, s[2:3]
	s_add_u32 m0, s4, 0x2400
	s_nop 0
	global_load_lds_dwordx4 v179, s[2:3]
	s_waitcnt lgkmcnt(8)
	s_barrier
	s_waitcnt lgkmcnt(0)
	s_setprio 1
	v_mfma_f32_32x32x16_bf16 v[114:129], v[192:195], v[130:133], v[114:129]
	v_mfma_f32_32x32x16_bf16 v[82:97], v[192:195], v[146:149], v[82:97]
	v_mfma_f32_32x32x16_bf16 v[114:129], v[196:199], v[134:137], v[114:129]
	v_mfma_f32_32x32x16_bf16 v[82:97], v[196:199], v[150:153], v[82:97]
	v_mfma_f32_32x32x16_bf16 v[114:129], v[208:211], v[138:141], v[114:129]
	v_mfma_f32_32x32x16_bf16 v[82:97], v[208:211], v[154:157], v[82:97]
	v_mfma_f32_32x32x16_bf16 v[114:129], v[218:221], v[142:145], v[114:129]
	v_mfma_f32_32x32x16_bf16 v[82:97], v[218:221], v[158:161], v[82:97]
	s_setprio 0
	s_barrier
	ds_read_b128 v[222:225], v250 offset:36864
	ds_read_b128 v[234:237], v251 offset:36864
	ds_read_b128 v[238:241], v252 offset:36864
	ds_read_b128 v[242:245], v233 offset:36864
	s_add_u32 s6, s6, 0x80
	s_addc_u32 s7, s7, 0
	s_add_u32 m0, s16, 0x8000
	s_nop 0
	global_load_lds_dwordx4 v228, s[6:7]
	s_add_u32 m0, s16, 0x8400
	s_nop 0
	global_load_lds_dwordx4 v214, s[6:7]
	s_barrier
	s_waitcnt lgkmcnt(0)
	s_setprio 1
	v_mfma_f32_32x32x16_bf16 v[98:113], v[222:225], v[130:133], v[98:113]
	v_mfma_f32_32x32x16_bf16 v[66:81], v[222:225], v[146:149], v[66:81]
	v_mfma_f32_32x32x16_bf16 v[98:113], v[234:237], v[134:137], v[98:113]
	v_mfma_f32_32x32x16_bf16 v[66:81], v[234:237], v[150:153], v[66:81]
	v_mfma_f32_32x32x16_bf16 v[98:113], v[238:241], v[138:141], v[98:113]
	v_mfma_f32_32x32x16_bf16 v[66:81], v[238:241], v[154:157], v[66:81]
	v_mfma_f32_32x32x16_bf16 v[98:113], v[242:245], v[142:145], v[98:113]
	v_mfma_f32_32x32x16_bf16 v[66:81], v[242:245], v[158:161], v[66:81]
	s_setprio 0
	s_barrier
	ds_read_b128 v[130:133], v246 offset:40960
	ds_read_b128 v[134:137], v247 offset:40960
	ds_read_b128 v[138:141], v248 offset:40960
	ds_read_b128 v[142:145], v249 offset:40960
	ds_read_b128 v[146:149], v246 offset:45056
	ds_read_b128 v[150:153], v247 offset:45056
	ds_read_b128 v[154:157], v248 offset:45056
	ds_read_b128 v[158:161], v249 offset:45056
	s_add_u32 s2, s2, 0x80
	s_addc_u32 s3, s3, 0
	s_add_u32 m0, s4, 0x8000
	s_nop 0
	global_load_lds_dwordx4 v226, s[2:3]
	s_add_u32 m0, s4, 0x8400
	s_nop 0
	global_load_lds_dwordx4 v227, s[2:3]
	s_barrier
	s_waitcnt lgkmcnt(0)
	s_setprio 1
	v_mfma_f32_32x32x16_bf16 v[50:65], v[192:195], v[130:133], v[50:65]
	v_mfma_f32_32x32x16_bf16 v[18:33], v[192:195], v[146:149], v[18:33]
	v_mfma_f32_32x32x16_bf16 v[50:65], v[196:199], v[134:137], v[50:65]
	v_mfma_f32_32x32x16_bf16 v[18:33], v[196:199], v[150:153], v[18:33]
	v_mfma_f32_32x32x16_bf16 v[50:65], v[208:211], v[138:141], v[50:65]
	v_mfma_f32_32x32x16_bf16 v[18:33], v[208:211], v[154:157], v[18:33]
	v_mfma_f32_32x32x16_bf16 v[50:65], v[218:221], v[142:145], v[50:65]
	v_mfma_f32_32x32x16_bf16 v[18:33], v[218:221], v[158:161], v[18:33]
	s_setprio 0
	s_barrier
	s_add_u32 m0, s16, 0x9000
	s_nop 0
	global_load_lds_dwordx4 v203, s[6:7]
	s_add_u32 m0, s16, 0x9400
	s_nop 0
	global_load_lds_dwordx4 v204, s[6:7]
	s_waitcnt vmcnt(6)
	s_barrier
	s_setprio 1
	v_mfma_f32_32x32x16_bf16 v[34:49], v[222:225], v[130:133], v[34:49]
	v_mfma_f32_32x32x16_bf16 v[2:17], v[222:225], v[146:149], v[2:17]
	v_mfma_f32_32x32x16_bf16 v[34:49], v[234:237], v[134:137], v[34:49]
	v_mfma_f32_32x32x16_bf16 v[2:17], v[234:237], v[150:153], v[2:17]
	v_mfma_f32_32x32x16_bf16 v[34:49], v[238:241], v[138:141], v[34:49]
	v_mfma_f32_32x32x16_bf16 v[2:17], v[238:241], v[154:157], v[2:17]
	v_mfma_f32_32x32x16_bf16 v[34:49], v[242:245], v[142:145], v[34:49]
	v_mfma_f32_32x32x16_bf16 v[2:17], v[242:245], v[158:161], v[2:17]
	s_setprio 0
	s_barrier
	s_add_i32 s17, s17, 2
	s_cmp_lt_u32 s17, 14
	s_cbranch_scc1 .Lggu_loop
	ds_read_b128 v[192:195], v250
	ds_read_b128 v[196:199], v251
	ds_read_b128 v[208:211], v252
	ds_read_b128 v[218:221], v233
	ds_read_b128 v[130:133], v246 offset:0
	ds_read_b128 v[134:137], v247 offset:0
	ds_read_b128 v[138:141], v248 offset:0
	ds_read_b128 v[142:145], v249 offset:0
	ds_read_b128 v[146:149], v246 offset:4096
	ds_read_b128 v[150:153], v247 offset:4096
	ds_read_b128 v[154:157], v248 offset:4096
	ds_read_b128 v[158:161], v249 offset:4096
	s_add_u32 m0, s4, 0xa000
	s_nop 0
	global_load_lds_dwordx4 v178, s[2:3]
	s_add_u32 m0, s4, 0xa400
	s_nop 0
	global_load_lds_dwordx4 v179, s[2:3]
	s_barrier
	s_waitcnt lgkmcnt(0)
	s_setprio 1
	v_mfma_f32_32x32x16_bf16 v[114:129], v[192:195], v[130:133], v[114:129]
	v_mfma_f32_32x32x16_bf16 v[82:97], v[192:195], v[146:149], v[82:97]
	v_mfma_f32_32x32x16_bf16 v[114:129], v[196:199], v[134:137], v[114:129]
	v_mfma_f32_32x32x16_bf16 v[82:97], v[196:199], v[150:153], v[82:97]
	v_mfma_f32_32x32x16_bf16 v[114:129], v[208:211], v[138:141], v[114:129]
	v_mfma_f32_32x32x16_bf16 v[82:97], v[208:211], v[154:157], v[82:97]
	v_mfma_f32_32x32x16_bf16 v[114:129], v[218:221], v[142:145], v[114:129]
	v_mfma_f32_32x32x16_bf16 v[82:97], v[218:221], v[158:161], v[82:97]
	s_setprio 0
	s_barrier
	ds_read_b128 v[222:225], v250 offset:4096
	ds_read_b128 v[234:237], v251 offset:4096
	ds_read_b128 v[238:241], v252 offset:4096
	ds_read_b128 v[242:245], v233 offset:4096
	s_barrier
	s_waitcnt lgkmcnt(0)
	s_setprio 1
	v_mfma_f32_32x32x16_bf16 v[98:113], v[222:225], v[130:133], v[98:113]
	v_mfma_f32_32x32x16_bf16 v[66:81], v[222:225], v[146:149], v[66:81]
	v_mfma_f32_32x32x16_bf16 v[98:113], v[234:237], v[134:137], v[98:113]
	v_mfma_f32_32x32x16_bf16 v[66:81], v[234:237], v[150:153], v[66:81]
	v_mfma_f32_32x32x16_bf16 v[98:113], v[238:241], v[138:141], v[98:113]
	v_mfma_f32_32x32x16_bf16 v[66:81], v[238:241], v[154:157], v[66:81]
	v_mfma_f32_32x32x16_bf16 v[98:113], v[242:245], v[142:145], v[98:113]
	v_mfma_f32_32x32x16_bf16 v[66:81], v[242:245], v[158:161], v[66:81]
	s_setprio 0
	s_barrier
	ds_read_b128 v[130:133], v246 offset:8192
	ds_read_b128 v[134:137], v247 offset:8192
	ds_read_b128 v[138:141], v248 offset:8192
	ds_read_b128 v[142:145], v249 offset:8192
	ds_read_b128 v[146:149], v246 offset:12288
	ds_read_b128 v[150:153], v247 offset:12288
	ds_read_b128 v[154:157], v248 offset:12288
	ds_read_b128 v[158:161], v249 offset:12288
	s_waitcnt vmcnt(4)
	s_barrier
	s_waitcnt lgkmcnt(0)
	s_setprio 1
	v_mfma_f32_32x32x16_bf16 v[50:65], v[192:195], v[130:133], v[50:65]
	v_mfma_f32_32x32x16_bf16 v[18:33], v[192:195], v[146:149], v[18:33]
	v_mfma_f32_32x32x16_bf16 v[50:65], v[196:199], v[134:137], v[50:65]
	v_mfma_f32_32x32x16_bf16 v[18:33], v[196:199], v[150:153], v[18:33]
	v_mfma_f32_32x32x16_bf16 v[50:65], v[208:211], v[138:141], v[50:65]
	v_mfma_f32_32x32x16_bf16 v[18:33], v[208:211], v[154:157], v[18:33]
	v_mfma_f32_32x32x16_bf16 v[50:65], v[218:221], v[142:145], v[50:65]
	v_mfma_f32_32x32x16_bf16 v[18:33], v[218:221], v[158:161], v[18:33]
	s_setprio 0
	s_setprio 1
	v_mfma_f32_32x32x16_bf16 v[34:49], v[222:225], v[130:133], v[34:49]
	v_mfma_f32_32x32x16_bf16 v[2:17], v[222:225], v[146:149], v[2:17]
	v_mfma_f32_32x32x16_bf16 v[34:49], v[234:237], v[134:137], v[34:49]
	v_mfma_f32_32x32x16_bf16 v[2:17], v[234:237], v[150:153], v[2:17]
	v_mfma_f32_32x32x16_bf16 v[34:49], v[238:241], v[138:141], v[34:49]
	v_mfma_f32_32x32x16_bf16 v[2:17], v[238:241], v[154:157], v[2:17]
	v_mfma_f32_32x32x16_bf16 v[34:49], v[242:245], v[142:145], v[34:49]
	v_mfma_f32_32x32x16_bf16 v[2:17], v[242:245], v[158:161], v[2:17]
	s_setprio 0
	s_barrier
	ds_read_b128 v[192:195], v250 offset:32768
	ds_read_b128 v[196:199], v251 offset:32768
	ds_read_b128 v[208:211], v252 offset:32768
	ds_read_b128 v[218:221], v233 offset:32768
	ds_read_b128 v[130:133], v246 offset:32768
	ds_read_b128 v[134:137], v247 offset:32768
	ds_read_b128 v[138:141], v248 offset:32768
	ds_read_b128 v[142:145], v249 offset:32768
	ds_read_b128 v[146:149], v246 offset:36864
	ds_read_b128 v[150:153], v247 offset:36864
	ds_read_b128 v[154:157], v248 offset:36864
	ds_read_b128 v[158:161], v249 offset:36864
	s_waitcnt vmcnt(2)
	s_barrier
	s_waitcnt lgkmcnt(0)
	s_setprio 1
	v_mfma_f32_32x32x16_bf16 v[114:129], v[192:195], v[130:133], v[114:129]
	v_mfma_f32_32x32x16_bf16 v[82:97], v[192:195], v[146:149], v[82:97]
	v_mfma_f32_32x32x16_bf16 v[114:129], v[196:199], v[134:137], v[114:129]
	v_mfma_f32_32x32x16_bf16 v[82:97], v[196:199], v[150:153], v[82:97]
	v_mfma_f32_32x32x16_bf16 v[114:129], v[208:211], v[138:141], v[114:129]
	v_mfma_f32_32x32x16_bf16 v[82:97], v[208:211], v[154:157], v[82:97]
	v_mfma_f32_32x32x16_bf16 v[114:129], v[218:221], v[142:145], v[114:129]
	v_mfma_f32_32x32x16_bf16 v[82:97], v[218:221], v[158:161], v[82:97]
	s_setprio 0
	s_barrier
	ds_read_b128 v[222:225], v250 offset:36864
	ds_read_b128 v[234:237], v251 offset:36864
	ds_read_b128 v[238:241], v252 offset:36864
	ds_read_b128 v[242:245], v233 offset:36864
	s_waitcnt vmcnt(0)
	s_barrier
	s_waitcnt lgkmcnt(0)
	s_setprio 1
	v_mfma_f32_32x32x16_bf16 v[98:113], v[222:225], v[130:133], v[98:113]
	v_mfma_f32_32x32x16_bf16 v[66:81], v[222:225], v[146:149], v[66:81]
	v_mfma_f32_32x32x16_bf16 v[98:113], v[234:237], v[134:137], v[98:113]
	v_mfma_f32_32x32x16_bf16 v[66:81], v[234:237], v[150:153], v[66:81]
	v_mfma_f32_32x32x16_bf16 v[98:113], v[238:241], v[138:141], v[98:113]
	v_mfma_f32_32x32x16_bf16 v[66:81], v[238:241], v[154:157], v[66:81]
	v_mfma_f32_32x32x16_bf16 v[98:113], v[242:245], v[142:145], v[98:113]
	v_mfma_f32_32x32x16_bf16 v[66:81], v[242:245], v[158:161], v[66:81]
	s_setprio 0
	s_barrier
	ds_read_b128 v[130:133], v246 offset:40960
	ds_read_b128 v[134:137], v247 offset:40960
	ds_read_b128 v[138:141], v248 offset:40960
	ds_read_b128 v[142:145], v249 offset:40960
	ds_read_b128 v[146:149], v246 offset:45056
	ds_read_b128 v[150:153], v247 offset:45056
	ds_read_b128 v[154:157], v248 offset:45056
	ds_read_b128 v[158:161], v249 offset:45056
	s_barrier
	s_waitcnt lgkmcnt(0)
	s_setprio 1
	v_mfma_f32_32x32x16_bf16 v[50:65], v[192:195], v[130:133], v[50:65]
	v_mfma_f32_32x32x16_bf16 v[18:33], v[192:195], v[146:149], v[18:33]
	v_mfma_f32_32x32x16_bf16 v[50:65], v[196:199], v[134:137], v[50:65]
	v_mfma_f32_32x32x16_bf16 v[18:33], v[196:199], v[150:153], v[18:33]
	v_mfma_f32_32x32x16_bf16 v[50:65], v[208:211], v[138:141], v[50:65]
	v_mfma_f32_32x32x16_bf16 v[18:33], v[208:211], v[154:157], v[18:33]
	v_mfma_f32_32x32x16_bf16 v[50:65], v[218:221], v[142:145], v[50:65]
	v_mfma_f32_32x32x16_bf16 v[18:33], v[218:221], v[158:161], v[18:33]
	s_setprio 0
	s_setprio 1
	v_mfma_f32_32x32x16_bf16 v[34:49], v[222:225], v[130:133], v[34:49]
	v_mfma_f32_32x32x16_bf16 v[2:17], v[222:225], v[146:149], v[2:17]
	v_mfma_f32_32x32x16_bf16 v[34:49], v[234:237], v[134:137], v[34:49]
	v_mfma_f32_32x32x16_bf16 v[2:17], v[234:237], v[150:153], v[2:17]
	v_mfma_f32_32x32x16_bf16 v[34:49], v[238:241], v[138:141], v[34:49]
	v_mfma_f32_32x32x16_bf16 v[2:17], v[238:241], v[154:157], v[2:17]
	v_mfma_f32_32x32x16_bf16 v[34:49], v[242:245], v[142:145], v[34:49]
	v_mfma_f32_32x32x16_bf16 v[2:17], v[242:245], v[158:161], v[2:17]
	s_setprio 0
	s_barrier
	s_cmp_lg_u32 s18, 0
	s_cbranch_scc1 .Lggu_nolag2
	s_barrier
